# v74 = v72 + past: key-block lists rebalanced by expected 8-wave rounds instead of counts (A={0,2,4,7,9,13,14}, B={1,3,5,6,8,10,11,12}; same items, each processed once)
# baseline (speedup 1.0000x reference)
.LBB0_254:
	s_lshr_b32 s0, 0x6295, s34
	s_and_b32 s0, s0, 1
	s_cselect_b64 s[16:17], 0, -1
	s_waitcnt vmcnt(10)
	v_cndmask_b32_e64 v0, 0, 1, s[16:17]
	v_cmp_ne_u32_e32 vcc, v0, v177
	s_cbranch_vccnz .LBB0_253
	s_lshl_b32 s0, s34, 15
	v_lshl_add_u64 v[24:25], v[152:153], 0, s[0:1]
	s_lshl_b32 s0, s34, 9
	v_mov_b32_e32 v133, v117
	v_lshl_add_u64 v[28:29], v[154:155], 0, s[0:1]
	v_lshl_add_u64 v[0:1], v[24:25], 0, v[132:133]
	v_mov_b32_e32 v135, v117
	s_barrier
	global_load_dwordx4 v[0:3], v[0:1], off
	v_lshl_add_u64 v[4:5], v[28:29], 0, v[134:135]
	v_mov_b32_e32 v137, v117
	global_load_dwordx4 v[4:7], v[4:5], off
	v_lshl_add_u64 v[8:9], v[24:25], 0, v[136:137]
	v_mov_b32_e32 v139, v117
	global_load_dwordx4 v[8:11], v[8:9], off
	v_lshl_add_u64 v[12:13], v[28:29], 0, v[138:139]
	v_mov_b32_e32 v141, v117
	global_load_dwordx4 v[12:15], v[12:13], off
	v_lshl_add_u64 v[16:17], v[24:25], 0, v[140:141]
	v_mov_b32_e32 v143, v117
	global_load_dwordx4 v[16:19], v[16:17], off
	v_lshl_add_u64 v[20:21], v[28:29], 0, v[142:143]
	v_mov_b32_e32 v149, v117
	global_load_dwordx4 v[20:23], v[20:21], off
	v_lshl_add_u64 v[24:25], v[24:25], 0, v[148:149]
	v_mov_b32_e32 v151, v117
	global_load_dwordx4 v[24:27], v[24:25], off
	v_lshl_add_u64 v[28:29], v[28:29], 0, v[150:151]
	global_load_dwordx4 v[28:31], v[28:29], off
	s_add_i32 s18, s34, s33
	s_ashr_i32 s19, s18, 31
	s_lshl_b64 s[16:17], s[18:19], 2
	s_add_u32 s16, s46, s16
	s_addc_u32 s17, s47, s17
	s_lshl_b64 s[18:19], s[18:19], 13
	s_add_u32 s18, s48, s18
	s_addc_u32 s19, s49, s19
	v_lshlrev_b32_e32 v232, 1, v175
	v_lshlrev_b32_e32 v233, 1, v176
	global_load_ushort v230, v232, s[18:19]
	global_load_ushort v231, v233, s[18:19]
	s_waitcnt vmcnt(9)
	ds_write_b128 v115, v[0:3]
	s_waitcnt vmcnt(8)
	ds_write_b128 v168, v[4:7]
	s_waitcnt vmcnt(7)
	ds_write_b128 v169, v[8:11]
	s_waitcnt vmcnt(6)
	ds_write_b128 v170, v[12:15]
	s_waitcnt vmcnt(5)
	ds_write_b128 v171, v[16:19]
	s_waitcnt vmcnt(4)
	ds_write_b128 v172, v[20:23]
	s_waitcnt vmcnt(3)
	ds_write_b128 v173, v[24:27]
	s_waitcnt vmcnt(2)
	ds_write_b128 v174, v[28:31]
	s_waitcnt lgkmcnt(0)
	s_waitcnt vmcnt(1)
	v_and_b32_e32 v137, 0xfff, v230
	v_lshlrev_b32_e32 v232, 7, v137
	v_mov_b32_e32 v233, 0
	v_lshl_add_u64 v[4:5], v[156:157], 0, v[232:233]
	global_load_dwordx4 v[0:3], v[4:5], off
	s_nop 0
	global_load_dwordx4 v[4:7], v[4:5], off offset:64
	s_waitcnt vmcnt(2)
	v_and_b32_e32 v139, 0xfff, v231
	v_lshlrev_b32_e32 v232, 7, v139
	v_lshl_add_u64 v[12:13], v[156:157], 0, v[232:233]
	global_load_dwordx4 v[8:11], v[12:13], off
	s_nop 0
	global_load_dwordx4 v[12:15], v[12:13], off offset:64
	s_barrier
	global_load_dword v133, v117, s[16:17]
	s_waitcnt vmcnt(0)
	v_add_u32_e32 v232, 31, v133
	v_ashrrev_i32_e32 v135, 5, v232
	v_cmp_lt_i32_e32 vcc, v196, v135
	s_and_saveexec_b64 s[16:17], vcc
	s_cbranch_execz .LBB0_252
	v_cmp_lt_i32_e64 s[20:21], v175, v133
	v_cmp_lt_i32_e64 s[24:25], v176, v133
	s_mov_b64 s[22:23], 0
	v_mov_b32_e32 v143, v196
	v_mov_b32_e32 v141, v230
	v_mov_b32_e32 v149, v231
	s_branch .LBB0_258
